# GEMM tiles: first K step's loads issued before the accumulators are cleared
# baseline (speedup 1.0000x reference)
.Lg2_ff2_tile:
	s_lshl_b32 s0, s64, 3
	s_add_i32 s38, s0, s68
	s_mov_b32 s69, s42
	s_mov_b32 s65, s43
	s_lshl_b32 s0, s38, 7
	s_mul_i32 s2, s69, 0x2000
	s_mul_hi_u32 s3, s69, 0x2000
	s_add_u32 s56, s26, s2
	s_addc_u32 s57, s27, s3
	s_add_u32 s56, s56, 0x0
	s_addc_u32 s57, s57, 0
	s_mul_i32 s2, s0, 0x2000
	s_mul_hi_u32 s3, s0, 0x2000
	s_add_u32 s58, s26, s2
	s_addc_u32 s59, s27, s3
	s_add_u32 s58, s58, 0x10740000
	s_addc_u32 s59, s59, 0
	s_mul_i32 s2, s69, 0x800
	s_mul_hi_u32 s3, s69, 0x800
	s_lshl_b32 s0, s0, 1
	s_add_u32 s2, s2, s0
	s_addc_u32 s3, s3, 0
	s_add_u32 s60, s26, s2
	s_addc_u32 s61, s27, s3
	s_add_u32 s60, s60, 0x11140000
	s_addc_u32 s61, s61, 0
	s_cmp_eq_u32 s65, 0
	s_cbranch_scc1 .Lg2_ff2_k16
	s_add_u32 s4, s56, 0x0
	s_addc_u32 s5, s57, 0
	s_add_u32 m0, s62, 0x0
	s_nop 0
	global_load_lds_dwordx4 v162, s[4:5]
	s_add_u32 s4, s56, 0x40000
	s_addc_u32 s5, s57, 0
	s_add_u32 m0, s62, 0x1000
	s_nop 0
	global_load_lds_dwordx4 v162, s[4:5]
	s_add_u32 s4, s56, 0x80000
	s_addc_u32 s5, s57, 0
	s_add_u32 m0, s62, 0x2000
	s_nop 0
	global_load_lds_dwordx4 v162, s[4:5]
	s_add_u32 s4, s56, 0xc0000
	s_addc_u32 s5, s57, 0
	s_add_u32 m0, s62, 0x3000
	s_nop 0
	global_load_lds_dwordx4 v162, s[4:5]
	s_add_u32 s4, s56, 0x100000
	s_addc_u32 s5, s57, 0
	s_add_u32 m0, s62, 0x4000
	s_nop 0
	global_load_lds_dwordx4 v162, s[4:5]
	s_add_u32 s4, s56, 0x140000
	s_addc_u32 s5, s57, 0
	s_add_u32 m0, s62, 0x5000
	s_nop 0
	global_load_lds_dwordx4 v162, s[4:5]
	s_add_u32 s4, s56, 0x180000
	s_addc_u32 s5, s57, 0
	s_add_u32 m0, s62, 0x6000
	s_nop 0
	global_load_lds_dwordx4 v162, s[4:5]
	s_add_u32 s4, s56, 0x1c0000
	s_addc_u32 s5, s57, 0
	s_add_u32 m0, s62, 0x7000
	s_nop 0
	global_load_lds_dwordx4 v162, s[4:5]
	s_cmp_gt_u32 s70, 1
	s_cbranch_scc1 .Lg2_ff2_nodma_0
	s_add_u32 s4, s56, 0x200000
	s_addc_u32 s5, s57, 0
	s_add_u32 m0, s62, 0x8000
	s_nop 0
	global_load_lds_dwordx4 v162, s[4:5]
.Lg2_ff2_nodma_0:
	global_load_dwordx4 v[184:187], v160, s[58:59] offset:0
	global_load_dwordx4 v[188:191], v160, s[58:59] offset:1024
	global_load_dwordx4 v[192:195], v161, s[58:59] offset:0
	global_load_dwordx4 v[196:199], v161, s[58:59] offset:1024
	v_mov_b32_e32 v0, 0
	v_mov_b32_e32 v1, 0
	v_mov_b32_e32 v2, 0
	v_mov_b32_e32 v3, 0
	v_mov_b32_e32 v4, 0
	v_mov_b32_e32 v5, 0
	v_mov_b32_e32 v6, 0
	v_mov_b32_e32 v7, 0
	v_mov_b32_e32 v8, 0
	v_mov_b32_e32 v9, 0
	v_mov_b32_e32 v10, 0
	v_mov_b32_e32 v11, 0
	v_mov_b32_e32 v12, 0
	v_mov_b32_e32 v13, 0
	v_mov_b32_e32 v14, 0
	v_mov_b32_e32 v15, 0
	v_mov_b32_e32 v16, 0
	v_mov_b32_e32 v17, 0
	v_mov_b32_e32 v18, 0
	v_mov_b32_e32 v19, 0
	v_mov_b32_e32 v20, 0
	v_mov_b32_e32 v21, 0
	v_mov_b32_e32 v22, 0
	v_mov_b32_e32 v23, 0
	v_mov_b32_e32 v24, 0
	v_mov_b32_e32 v25, 0
	v_mov_b32_e32 v26, 0
	v_mov_b32_e32 v27, 0
	v_mov_b32_e32 v28, 0
	v_mov_b32_e32 v29, 0
	v_mov_b32_e32 v30, 0
	v_mov_b32_e32 v31, 0
	v_mov_b32_e32 v32, 0
	v_mov_b32_e32 v33, 0
	v_mov_b32_e32 v34, 0
	v_mov_b32_e32 v35, 0
	v_mov_b32_e32 v36, 0
	v_mov_b32_e32 v37, 0
	v_mov_b32_e32 v38, 0
	v_mov_b32_e32 v39, 0
	v_mov_b32_e32 v40, 0
	v_mov_b32_e32 v41, 0
	v_mov_b32_e32 v42, 0
	v_mov_b32_e32 v43, 0
	v_mov_b32_e32 v44, 0
	v_mov_b32_e32 v45, 0
	v_mov_b32_e32 v46, 0
	v_mov_b32_e32 v47, 0
	v_mov_b32_e32 v48, 0
	v_mov_b32_e32 v49, 0
	v_mov_b32_e32 v50, 0
	v_mov_b32_e32 v51, 0
	v_mov_b32_e32 v52, 0
	v_mov_b32_e32 v53, 0
	v_mov_b32_e32 v54, 0
	v_mov_b32_e32 v55, 0
	v_mov_b32_e32 v56, 0
	v_mov_b32_e32 v57, 0
	v_mov_b32_e32 v58, 0
	v_mov_b32_e32 v59, 0
	v_mov_b32_e32 v60, 0
	v_mov_b32_e32 v61, 0
	v_mov_b32_e32 v62, 0
	v_mov_b32_e32 v63, 0
	v_mov_b32_e32 v64, 0
	v_mov_b32_e32 v65, 0
	v_mov_b32_e32 v66, 0
	v_mov_b32_e32 v67, 0
	v_mov_b32_e32 v68, 0
	v_mov_b32_e32 v69, 0
	v_mov_b32_e32 v70, 0
	v_mov_b32_e32 v71, 0
	v_mov_b32_e32 v72, 0
	v_mov_b32_e32 v73, 0
	v_mov_b32_e32 v74, 0
	v_mov_b32_e32 v75, 0
	v_mov_b32_e32 v76, 0
	v_mov_b32_e32 v77, 0
	v_mov_b32_e32 v78, 0
	v_mov_b32_e32 v79, 0
	v_mov_b32_e32 v80, 0
	v_mov_b32_e32 v81, 0
	v_mov_b32_e32 v82, 0
	v_mov_b32_e32 v83, 0
	v_mov_b32_e32 v84, 0
	v_mov_b32_e32 v85, 0
	v_mov_b32_e32 v86, 0
	v_mov_b32_e32 v87, 0
	v_mov_b32_e32 v88, 0
	v_mov_b32_e32 v89, 0
	v_mov_b32_e32 v90, 0
	v_mov_b32_e32 v91, 0
	v_mov_b32_e32 v92, 0
	v_mov_b32_e32 v93, 0
	v_mov_b32_e32 v94, 0
	v_mov_b32_e32 v95, 0
	v_mov_b32_e32 v96, 0
	v_mov_b32_e32 v97, 0
	v_mov_b32_e32 v98, 0
	v_mov_b32_e32 v99, 0
	v_mov_b32_e32 v100, 0
	v_mov_b32_e32 v101, 0
	v_mov_b32_e32 v102, 0
	v_mov_b32_e32 v103, 0
	v_mov_b32_e32 v104, 0
	v_mov_b32_e32 v105, 0
	v_mov_b32_e32 v106, 0
	v_mov_b32_e32 v107, 0
	v_mov_b32_e32 v108, 0
	v_mov_b32_e32 v109, 0
	v_mov_b32_e32 v110, 0
	v_mov_b32_e32 v111, 0
	v_mov_b32_e32 v112, 0
	v_mov_b32_e32 v113, 0
	v_mov_b32_e32 v114, 0
	v_mov_b32_e32 v115, 0
	v_mov_b32_e32 v116, 0
	v_mov_b32_e32 v117, 0
	v_mov_b32_e32 v118, 0
	v_mov_b32_e32 v119, 0
	v_mov_b32_e32 v120, 0
	v_mov_b32_e32 v121, 0
	v_mov_b32_e32 v122, 0
	v_mov_b32_e32 v123, 0
	v_mov_b32_e32 v124, 0
	v_mov_b32_e32 v125, 0
	v_mov_b32_e32 v126, 0
	v_mov_b32_e32 v127, 0
	v_mov_b32_e32 v128, 0
	v_mov_b32_e32 v129, 0
	v_mov_b32_e32 v130, 0
	v_mov_b32_e32 v131, 0
	v_mov_b32_e32 v132, 0
	v_mov_b32_e32 v133, 0
	v_mov_b32_e32 v134, 0
	v_mov_b32_e32 v135, 0
	s_mov_b32 s63, 0

.Lg2_ff2_k16:
	s_add_u32 s4, s56, 0x0
	s_addc_u32 s5, s57, 0
	s_add_u32 m0, s62, 0x0
	s_nop 0
	global_load_lds_dwordx4 v162, s[4:5]
	s_add_u32 s4, s56, 0x40000
	s_addc_u32 s5, s57, 0
	s_add_u32 m0, s62, 0x1000
	s_nop 0
	global_load_lds_dwordx4 v162, s[4:5]
	s_add_u32 s4, s56, 0x80000
	s_addc_u32 s5, s57, 0
	s_add_u32 m0, s62, 0x2000
	s_nop 0
	global_load_lds_dwordx4 v162, s[4:5]
	s_add_u32 s4, s56, 0xc0000
	s_addc_u32 s5, s57, 0
	s_add_u32 m0, s62, 0x3000
	s_nop 0
	global_load_lds_dwordx4 v162, s[4:5]
	s_add_u32 s4, s56, 0x100000
	s_addc_u32 s5, s57, 0
	s_add_u32 m0, s62, 0x4000
	s_nop 0
	global_load_lds_dwordx4 v162, s[4:5]
	s_add_u32 s4, s56, 0x140000
	s_addc_u32 s5, s57, 0
	s_add_u32 m0, s62, 0x5000
	s_nop 0
	global_load_lds_dwordx4 v162, s[4:5]
	s_add_u32 s4, s56, 0x180000
	s_addc_u32 s5, s57, 0
	s_add_u32 m0, s62, 0x6000
	s_nop 0
	global_load_lds_dwordx4 v162, s[4:5]
	s_add_u32 s4, s56, 0x1c0000
	s_addc_u32 s5, s57, 0
	s_add_u32 m0, s62, 0x7000
	s_nop 0
	global_load_lds_dwordx4 v162, s[4:5]
	global_load_dwordx4 v[184:187], v160, s[58:59] offset:0
	global_load_dwordx4 v[188:191], v160, s[58:59] offset:1024
	global_load_dwordx4 v[192:195], v161, s[58:59] offset:0
	global_load_dwordx4 v[196:199], v161, s[58:59] offset:1024
	v_mov_b32_e32 v0, 0
	v_mov_b32_e32 v1, 0
	v_mov_b32_e32 v2, 0
	v_mov_b32_e32 v3, 0
	v_mov_b32_e32 v4, 0
	v_mov_b32_e32 v5, 0
	v_mov_b32_e32 v6, 0
	v_mov_b32_e32 v7, 0
	v_mov_b32_e32 v8, 0
	v_mov_b32_e32 v9, 0
	v_mov_b32_e32 v10, 0
	v_mov_b32_e32 v11, 0
	v_mov_b32_e32 v12, 0
	v_mov_b32_e32 v13, 0
	v_mov_b32_e32 v14, 0
	v_mov_b32_e32 v15, 0
	v_mov_b32_e32 v16, 0
	v_mov_b32_e32 v17, 0
	v_mov_b32_e32 v18, 0
	v_mov_b32_e32 v19, 0
	v_mov_b32_e32 v20, 0
	v_mov_b32_e32 v21, 0
	v_mov_b32_e32 v22, 0
	v_mov_b32_e32 v23, 0
	v_mov_b32_e32 v24, 0
	v_mov_b32_e32 v25, 0
	v_mov_b32_e32 v26, 0
	v_mov_b32_e32 v27, 0
	v_mov_b32_e32 v28, 0
	v_mov_b32_e32 v29, 0
	v_mov_b32_e32 v30, 0
	v_mov_b32_e32 v31, 0
	v_mov_b32_e32 v32, 0
	v_mov_b32_e32 v33, 0
	v_mov_b32_e32 v34, 0
	v_mov_b32_e32 v35, 0
	v_mov_b32_e32 v36, 0
	v_mov_b32_e32 v37, 0
	v_mov_b32_e32 v38, 0
	v_mov_b32_e32 v39, 0
	v_mov_b32_e32 v40, 0
	v_mov_b32_e32 v41, 0
	v_mov_b32_e32 v42, 0
	v_mov_b32_e32 v43, 0
	v_mov_b32_e32 v44, 0
	v_mov_b32_e32 v45, 0
	v_mov_b32_e32 v46, 0
	v_mov_b32_e32 v47, 0
	v_mov_b32_e32 v48, 0
	v_mov_b32_e32 v49, 0
	v_mov_b32_e32 v50, 0
	v_mov_b32_e32 v51, 0
	v_mov_b32_e32 v52, 0
	v_mov_b32_e32 v53, 0
	v_mov_b32_e32 v54, 0
	v_mov_b32_e32 v55, 0
	v_mov_b32_e32 v56, 0
	v_mov_b32_e32 v57, 0
	v_mov_b32_e32 v58, 0
	v_mov_b32_e32 v59, 0
	v_mov_b32_e32 v60, 0
	v_mov_b32_e32 v61, 0
	v_mov_b32_e32 v62, 0
	v_mov_b32_e32 v63, 0
	v_mov_b32_e32 v64, 0
	v_mov_b32_e32 v65, 0
	v_mov_b32_e32 v66, 0
	v_mov_b32_e32 v67, 0
	v_mov_b32_e32 v68, 0
	v_mov_b32_e32 v69, 0
	v_mov_b32_e32 v70, 0
	v_mov_b32_e32 v71, 0
	v_mov_b32_e32 v72, 0
	v_mov_b32_e32 v73, 0
	v_mov_b32_e32 v74, 0
	v_mov_b32_e32 v75, 0
	v_mov_b32_e32 v76, 0
	v_mov_b32_e32 v77, 0
	v_mov_b32_e32 v78, 0
	v_mov_b32_e32 v79, 0
	v_mov_b32_e32 v80, 0
	v_mov_b32_e32 v81, 0
	v_mov_b32_e32 v82, 0
	v_mov_b32_e32 v83, 0
	v_mov_b32_e32 v84, 0
	v_mov_b32_e32 v85, 0
	v_mov_b32_e32 v86, 0
	v_mov_b32_e32 v87, 0
	v_mov_b32_e32 v88, 0
	v_mov_b32_e32 v89, 0
	v_mov_b32_e32 v90, 0
	v_mov_b32_e32 v91, 0
	v_mov_b32_e32 v92, 0
	v_mov_b32_e32 v93, 0
	v_mov_b32_e32 v94, 0
	v_mov_b32_e32 v95, 0
	v_mov_b32_e32 v96, 0
	v_mov_b32_e32 v97, 0
	v_mov_b32_e32 v98, 0
	v_mov_b32_e32 v99, 0
	v_mov_b32_e32 v100, 0
	v_mov_b32_e32 v101, 0
	v_mov_b32_e32 v102, 0
	v_mov_b32_e32 v103, 0
	v_mov_b32_e32 v104, 0
	v_mov_b32_e32 v105, 0
	v_mov_b32_e32 v106, 0
	v_mov_b32_e32 v107, 0
	v_mov_b32_e32 v108, 0
	v_mov_b32_e32 v109, 0
	v_mov_b32_e32 v110, 0
	v_mov_b32_e32 v111, 0
	v_mov_b32_e32 v112, 0
	v_mov_b32_e32 v113, 0
	v_mov_b32_e32 v114, 0
	v_mov_b32_e32 v115, 0
	v_mov_b32_e32 v116, 0
	v_mov_b32_e32 v117, 0
	v_mov_b32_e32 v118, 0
	v_mov_b32_e32 v119, 0
	v_mov_b32_e32 v120, 0
	v_mov_b32_e32 v121, 0
	v_mov_b32_e32 v122, 0
	v_mov_b32_e32 v123, 0
	v_mov_b32_e32 v124, 0
	v_mov_b32_e32 v125, 0
	v_mov_b32_e32 v126, 0
	v_mov_b32_e32 v127, 0
	s_mov_b32 s63, 0

.Lg2_ff1_tile:
	s_lshl_b32 s0, s64, 3
	s_add_i32 s38, s0, s68
	s_mov_b32 s69, s42
	s_mov_b32 s65, s43
	s_lshl_b32 s0, s38, 7
	s_mul_i32 s2, s69, 0x800
	s_mul_hi_u32 s3, s69, 0x800
	s_add_u32 s56, s26, s2
	s_addc_u32 s57, s27, s3
	s_add_u32 s56, s56, 0x13240000
	s_addc_u32 s57, s57, 0
	s_mul_i32 s2, s0, 0x800
	s_mul_hi_u32 s3, s0, 0x800
	s_add_u32 s58, s26, s2
	s_addc_u32 s59, s27, s3
	s_add_u32 s58, s58, 0xff40000
	s_addc_u32 s59, s59, 0
	s_mul_i32 s2, s69, 0x2000
	s_mul_hi_u32 s3, s69, 0x2000
	s_lshl_b32 s0, s0, 1
	s_add_u32 s2, s2, s0
	s_addc_u32 s3, s3, 0
	s_add_u32 s60, s26, s2
	s_addc_u32 s61, s27, s3
	s_add_u32 s60, s60, 0x0
	s_addc_u32 s61, s61, 0
	s_cmp_eq_u32 s65, 0
	s_cbranch_scc1 .Lg2_ff1_k16
	s_add_u32 s4, s56, 0x0
	s_addc_u32 s5, s57, 0
	s_add_u32 m0, s62, 0x0
	s_nop 0
	global_load_lds_dwordx4 v162, s[4:5]
	s_add_u32 s4, s56, 0x10000
	s_addc_u32 s5, s57, 0
	s_add_u32 m0, s62, 0x1000
	s_nop 0
	global_load_lds_dwordx4 v162, s[4:5]
	s_add_u32 s4, s56, 0x20000
	s_addc_u32 s5, s57, 0
	s_add_u32 m0, s62, 0x2000
	s_nop 0
	global_load_lds_dwordx4 v162, s[4:5]
	s_add_u32 s4, s56, 0x30000
	s_addc_u32 s5, s57, 0
	s_add_u32 m0, s62, 0x3000
	s_nop 0
	global_load_lds_dwordx4 v162, s[4:5]
	s_add_u32 s4, s56, 0x40000
	s_addc_u32 s5, s57, 0
	s_add_u32 m0, s62, 0x4000
	s_nop 0
	global_load_lds_dwordx4 v162, s[4:5]
	s_add_u32 s4, s56, 0x50000
	s_addc_u32 s5, s57, 0
	s_add_u32 m0, s62, 0x5000
	s_nop 0
	global_load_lds_dwordx4 v162, s[4:5]
	s_add_u32 s4, s56, 0x60000
	s_addc_u32 s5, s57, 0
	s_add_u32 m0, s62, 0x6000
	s_nop 0
	global_load_lds_dwordx4 v162, s[4:5]
	s_add_u32 s4, s56, 0x70000
	s_addc_u32 s5, s57, 0
	s_add_u32 m0, s62, 0x7000
	s_nop 0
	global_load_lds_dwordx4 v162, s[4:5]
	s_cmp_gt_u32 s70, 1
	s_cbranch_scc1 .Lg2_ff1_nodma_0
	s_add_u32 s4, s56, 0x80000
	s_addc_u32 s5, s57, 0
	s_add_u32 m0, s62, 0x8000
	s_nop 0
	global_load_lds_dwordx4 v162, s[4:5]

.Lg2_ff1_k16:
	s_add_u32 s4, s56, 0x0
	s_addc_u32 s5, s57, 0
	s_add_u32 m0, s62, 0x0
	s_nop 0
	global_load_lds_dwordx4 v162, s[4:5]
	s_add_u32 s4, s56, 0x10000
	s_addc_u32 s5, s57, 0
	s_add_u32 m0, s62, 0x1000
	s_nop 0
	global_load_lds_dwordx4 v162, s[4:5]
	s_add_u32 s4, s56, 0x20000
	s_addc_u32 s5, s57, 0
	s_add_u32 m0, s62, 0x2000
	s_nop 0
	global_load_lds_dwordx4 v162, s[4:5]
	s_add_u32 s4, s56, 0x30000
	s_addc_u32 s5, s57, 0
	s_add_u32 m0, s62, 0x3000
	s_nop 0
	global_load_lds_dwordx4 v162, s[4:5]
	s_add_u32 s4, s56, 0x40000
	s_addc_u32 s5, s57, 0
	s_add_u32 m0, s62, 0x4000
	s_nop 0
	global_load_lds_dwordx4 v162, s[4:5]
	s_add_u32 s4, s56, 0x50000
	s_addc_u32 s5, s57, 0
	s_add_u32 m0, s62, 0x5000
	s_nop 0
	global_load_lds_dwordx4 v162, s[4:5]
	s_add_u32 s4, s56, 0x60000
	s_addc_u32 s5, s57, 0
	s_add_u32 m0, s62, 0x6000
	s_nop 0
	global_load_lds_dwordx4 v162, s[4:5]
	s_add_u32 s4, s56, 0x70000
	s_addc_u32 s5, s57, 0
	s_add_u32 m0, s62, 0x7000
	s_nop 0
	global_load_lds_dwordx4 v162, s[4:5]
	global_load_dwordx4 v[184:187], v160, s[58:59] offset:0
	global_load_dwordx4 v[188:191], v160, s[58:59] offset:1024
	global_load_dwordx4 v[192:195], v161, s[58:59] offset:0
	global_load_dwordx4 v[196:199], v161, s[58:59] offset:1024
	v_mov_b32_e32 v0, 0
	v_mov_b32_e32 v1, 0
	v_mov_b32_e32 v2, 0
	v_mov_b32_e32 v3, 0
	v_mov_b32_e32 v4, 0
	v_mov_b32_e32 v5, 0
	v_mov_b32_e32 v6, 0
	v_mov_b32_e32 v7, 0
	v_mov_b32_e32 v8, 0
	v_mov_b32_e32 v9, 0
	v_mov_b32_e32 v10, 0
	v_mov_b32_e32 v11, 0
	v_mov_b32_e32 v12, 0
	v_mov_b32_e32 v13, 0
	v_mov_b32_e32 v14, 0
	v_mov_b32_e32 v15, 0
	v_mov_b32_e32 v16, 0
	v_mov_b32_e32 v17, 0
	v_mov_b32_e32 v18, 0
	v_mov_b32_e32 v19, 0
	v_mov_b32_e32 v20, 0
	v_mov_b32_e32 v21, 0
	v_mov_b32_e32 v22, 0
	v_mov_b32_e32 v23, 0
	v_mov_b32_e32 v24, 0
	v_mov_b32_e32 v25, 0
	v_mov_b32_e32 v26, 0
	v_mov_b32_e32 v27, 0
	v_mov_b32_e32 v28, 0
	v_mov_b32_e32 v29, 0
	v_mov_b32_e32 v30, 0
	v_mov_b32_e32 v31, 0
	v_mov_b32_e32 v32, 0
	v_mov_b32_e32 v33, 0
	v_mov_b32_e32 v34, 0
	v_mov_b32_e32 v35, 0
	v_mov_b32_e32 v36, 0
	v_mov_b32_e32 v37, 0
	v_mov_b32_e32 v38, 0
	v_mov_b32_e32 v39, 0
	v_mov_b32_e32 v40, 0
	v_mov_b32_e32 v41, 0
	v_mov_b32_e32 v42, 0
	v_mov_b32_e32 v43, 0
	v_mov_b32_e32 v44, 0
	v_mov_b32_e32 v45, 0
	v_mov_b32_e32 v46, 0
	v_mov_b32_e32 v47, 0
	v_mov_b32_e32 v48, 0
	v_mov_b32_e32 v49, 0
	v_mov_b32_e32 v50, 0
	v_mov_b32_e32 v51, 0
	v_mov_b32_e32 v52, 0
	v_mov_b32_e32 v53, 0
	v_mov_b32_e32 v54, 0
	v_mov_b32_e32 v55, 0
	v_mov_b32_e32 v56, 0
	v_mov_b32_e32 v57, 0
	v_mov_b32_e32 v58, 0
	v_mov_b32_e32 v59, 0
	v_mov_b32_e32 v60, 0
	v_mov_b32_e32 v61, 0
	v_mov_b32_e32 v62, 0
	v_mov_b32_e32 v63, 0
	v_mov_b32_e32 v64, 0
	v_mov_b32_e32 v65, 0
	v_mov_b32_e32 v66, 0
	v_mov_b32_e32 v67, 0
	v_mov_b32_e32 v68, 0
	v_mov_b32_e32 v69, 0
	v_mov_b32_e32 v70, 0
	v_mov_b32_e32 v71, 0
	v_mov_b32_e32 v72, 0
	v_mov_b32_e32 v73, 0
	v_mov_b32_e32 v74, 0
	v_mov_b32_e32 v75, 0
	v_mov_b32_e32 v76, 0
	v_mov_b32_e32 v77, 0
	v_mov_b32_e32 v78, 0
	v_mov_b32_e32 v79, 0
	v_mov_b32_e32 v80, 0
	v_mov_b32_e32 v81, 0
	v_mov_b32_e32 v82, 0
	v_mov_b32_e32 v83, 0
	v_mov_b32_e32 v84, 0
	v_mov_b32_e32 v85, 0
	v_mov_b32_e32 v86, 0
	v_mov_b32_e32 v87, 0
	v_mov_b32_e32 v88, 0
	v_mov_b32_e32 v89, 0
	v_mov_b32_e32 v90, 0
	v_mov_b32_e32 v91, 0
	v_mov_b32_e32 v92, 0
	v_mov_b32_e32 v93, 0
	v_mov_b32_e32 v94, 0
	v_mov_b32_e32 v95, 0
	v_mov_b32_e32 v96, 0
	v_mov_b32_e32 v97, 0
	v_mov_b32_e32 v98, 0
	v_mov_b32_e32 v99, 0
	v_mov_b32_e32 v100, 0
	v_mov_b32_e32 v101, 0
	v_mov_b32_e32 v102, 0
	v_mov_b32_e32 v103, 0
	v_mov_b32_e32 v104, 0
	v_mov_b32_e32 v105, 0
	v_mov_b32_e32 v106, 0
	v_mov_b32_e32 v107, 0
	v_mov_b32_e32 v108, 0
	v_mov_b32_e32 v109, 0
	v_mov_b32_e32 v110, 0
	v_mov_b32_e32 v111, 0
	v_mov_b32_e32 v112, 0
	v_mov_b32_e32 v113, 0
	v_mov_b32_e32 v114, 0
	v_mov_b32_e32 v115, 0
	v_mov_b32_e32 v116, 0
	v_mov_b32_e32 v117, 0
	v_mov_b32_e32 v118, 0
	v_mov_b32_e32 v119, 0
	v_mov_b32_e32 v120, 0
	v_mov_b32_e32 v121, 0
	v_mov_b32_e32 v122, 0
	v_mov_b32_e32 v123, 0
	v_mov_b32_e32 v124, 0
	v_mov_b32_e32 v125, 0
	v_mov_b32_e32 v126, 0
	v_mov_b32_e32 v127, 0
	s_mov_b32 s63, 0

.Lg2_out_tile:
	s_lshl_b32 s0, s64, 3
	s_add_i32 s38, s0, s68
	s_mov_b32 s69, s42
	s_mov_b32 s65, s43
	s_lshl_b32 s0, s38, 7
	s_mul_i32 s2, s69, 0x800
	s_mul_hi_u32 s3, s69, 0x800
	s_add_u32 s56, s26, s2
	s_addc_u32 s57, s27, s3
	s_add_u32 s56, s56, 0x13240000
	s_addc_u32 s57, s57, 0
	s_mul_i32 s2, s0, 0x800
	s_mul_hi_u32 s3, s0, 0x800
	s_add_u32 s58, s26, s2
	s_addc_u32 s59, s27, s3
	s_add_u32 s58, s58, 0xfd40000
	s_addc_u32 s59, s59, 0
	s_mul_i32 s2, s69, 0x800
	s_mul_hi_u32 s3, s69, 0x800
	s_lshl_b32 s0, s0, 1
	s_add_u32 s2, s2, s0
	s_addc_u32 s3, s3, 0
	s_add_u32 s60, s26, s2
	s_addc_u32 s61, s27, s3
	s_add_u32 s60, s60, 0x11140000
	s_addc_u32 s61, s61, 0
	s_cmp_eq_u32 s65, 0
	s_cbranch_scc1 .Lg2_out_k16
	s_add_u32 s4, s56, 0x0
	s_addc_u32 s5, s57, 0
	s_add_u32 m0, s62, 0x0
	s_nop 0
	global_load_lds_dwordx4 v162, s[4:5]
	s_add_u32 s4, s56, 0x10000
	s_addc_u32 s5, s57, 0
	s_add_u32 m0, s62, 0x1000
	s_nop 0
	global_load_lds_dwordx4 v162, s[4:5]
	s_add_u32 s4, s56, 0x20000
	s_addc_u32 s5, s57, 0
	s_add_u32 m0, s62, 0x2000
	s_nop 0
	global_load_lds_dwordx4 v162, s[4:5]
	s_add_u32 s4, s56, 0x30000
	s_addc_u32 s5, s57, 0
	s_add_u32 m0, s62, 0x3000
	s_nop 0
	global_load_lds_dwordx4 v162, s[4:5]
	s_add_u32 s4, s56, 0x40000
	s_addc_u32 s5, s57, 0
	s_add_u32 m0, s62, 0x4000
	s_nop 0
	global_load_lds_dwordx4 v162, s[4:5]
	s_add_u32 s4, s56, 0x50000
	s_addc_u32 s5, s57, 0
	s_add_u32 m0, s62, 0x5000
	s_nop 0
	global_load_lds_dwordx4 v162, s[4:5]
	s_add_u32 s4, s56, 0x60000
	s_addc_u32 s5, s57, 0
	s_add_u32 m0, s62, 0x6000
	s_nop 0
	global_load_lds_dwordx4 v162, s[4:5]
	s_add_u32 s4, s56, 0x70000
	s_addc_u32 s5, s57, 0
	s_add_u32 m0, s62, 0x7000
	s_nop 0
	global_load_lds_dwordx4 v162, s[4:5]
	s_cmp_gt_u32 s70, 1
	s_cbranch_scc1 .Lg2_out_nodma_0
	s_add_u32 s4, s56, 0x80000
	s_addc_u32 s5, s57, 0
	s_add_u32 m0, s62, 0x8000
	s_nop 0
	global_load_lds_dwordx4 v162, s[4:5]

.Lg2_win_tile:
	s_lshl_b32 s0, s64, 3
	s_add_i32 s38, s0, s68
	s_mov_b32 s69, s42
	s_mov_b32 s65, s43
	s_lshl_b32 s0, s38, 7
	s_mul_i32 s2, s69, 0x800
	s_mul_hi_u32 s3, s69, 0x800
	s_add_u32 s56, s26, s2
	s_addc_u32 s57, s27, s3
	s_add_u32 s56, s56, 0x11140000
	s_addc_u32 s57, s57, 0
	s_mul_i32 s2, s0, 0x800
	s_mul_hi_u32 s3, s0, 0x800
	s_add_u32 s58, s26, s2
	s_addc_u32 s59, s27, s3
	s_add_u32 s58, s58, 0xeb20000
	s_addc_u32 s59, s59, 0
	s_mul_i32 s2, s69, 0x3900
	s_mul_hi_u32 s3, s69, 0x3900
	s_lshl_b32 s0, s0, 1
	s_add_u32 s2, s2, s0
	s_addc_u32 s3, s3, 0
	s_add_u32 s60, s26, s2
	s_addc_u32 s61, s27, s3
	s_add_u32 s60, s60, 0x0
	s_addc_u32 s61, s61, 0
	s_cmp_eq_u32 s65, 0
	s_cbranch_scc1 .Lg2_win_k16
	s_add_u32 s4, s56, 0x0
	s_addc_u32 s5, s57, 0
	s_add_u32 m0, s62, 0x0
	s_nop 0
	global_load_lds_dwordx4 v162, s[4:5]
	s_add_u32 s4, s56, 0x10000
	s_addc_u32 s5, s57, 0
	s_add_u32 m0, s62, 0x1000
	s_nop 0
	global_load_lds_dwordx4 v162, s[4:5]
	s_add_u32 s4, s56, 0x20000
	s_addc_u32 s5, s57, 0
	s_add_u32 m0, s62, 0x2000
	s_nop 0
	global_load_lds_dwordx4 v162, s[4:5]
	s_add_u32 s4, s56, 0x30000
	s_addc_u32 s5, s57, 0
	s_add_u32 m0, s62, 0x3000
	s_nop 0
	global_load_lds_dwordx4 v162, s[4:5]
	s_add_u32 s4, s56, 0x40000
	s_addc_u32 s5, s57, 0
	s_add_u32 m0, s62, 0x4000
	s_nop 0
	global_load_lds_dwordx4 v162, s[4:5]
	s_add_u32 s4, s56, 0x50000
	s_addc_u32 s5, s57, 0
	s_add_u32 m0, s62, 0x5000
	s_nop 0
	global_load_lds_dwordx4 v162, s[4:5]
	s_add_u32 s4, s56, 0x60000
	s_addc_u32 s5, s57, 0
	s_add_u32 m0, s62, 0x6000
	s_nop 0
	global_load_lds_dwordx4 v162, s[4:5]
	s_add_u32 s4, s56, 0x70000
	s_addc_u32 s5, s57, 0
	s_add_u32 m0, s62, 0x7000
	s_nop 0
	global_load_lds_dwordx4 v162, s[4:5]
	s_cmp_gt_u32 s70, 1
	s_cbranch_scc1 .Lg2_win_nodma_0
	s_add_u32 s4, s56, 0x80000
	s_addc_u32 s5, s57, 0
	s_add_u32 m0, s62, 0x8000
	s_nop 0
	global_load_lds_dwordx4 v162, s[4:5]

.Lg2_win_next:
	s_add_i32 s64, s64, 1
	s_cmp_lt_u32 s64, 7
	s_cbranch_scc1 .Lg2_win_tile
	v_lshrrev_b32_e32 v4, 6, v163
	v_and_b32_e32 v5, 63, v163
	v_and_b32_e32 v6, 15, v5
	v_lshrrev_b32_e32 v7, 4, v5
	v_lshlrev_b32_e32 v11, 1, v4
	s_mov_b32 s2, 0x8000
	v_mul_lo_u32 v12, v11, s2
	v_lshl_add_u32 v160, v5, 4, v12
	v_add_u32_e32 v161, 0x8000, v160
	v_lshrrev_b32_e32 v12, 1, v7
	v_lshl_add_u32 v12, v11, 1, v12
	v_and_b32_e32 v13, 1, v7
	v_lshlrev_b32_e32 v13, 3, v13
	v_lshl_add_u32 v14, v6, 8, v13
	v_xor_b32_e32 v15, v12, v6
	v_lshlrev_b32_e32 v15, 4, v15
	v_add_u32_e32 v212, v14, v15
	v_add_u32_e32 v12, 2, v12
	v_xor_b32_e32 v15, v12, v6
	v_lshlrev_b32_e32 v15, 4, v15
	v_add_u32_e32 v213, v14, v15
	v_add_u32_e32 v253, 0x8000, v212
	v_add_u32_e32 v254, 0x8000, v213
	s_mov_b32 s38, 56
	s_lshl_b32 s0, s68, 5
	s_add_i32 s69, s42, s0
	s_cmp_eq_u32 s68, 7
	s_cselect_b32 s0, 1, 0
	s_and_b32 s65, s0, s43
	s_lshl_b32 s0, s38, 7
	s_mul_i32 s2, s69, 0x800
	s_mul_hi_u32 s3, s69, 0x800
	s_add_u32 s56, s26, s2
	s_addc_u32 s57, s27, s3
	s_add_u32 s56, s56, 0x11140000
	s_addc_u32 s57, s57, 0
	s_mul_i32 s2, s0, 0x800
	s_mul_hi_u32 s3, s0, 0x800
	s_add_u32 s58, s26, s2
	s_addc_u32 s59, s27, s3
	s_add_u32 s58, s58, 0xeb20000
	s_addc_u32 s59, s59, 0
	s_mul_i32 s2, s69, 0x3900
	s_mul_hi_u32 s3, s69, 0x3900
	s_lshl_b32 s0, s0, 1
	s_add_u32 s2, s2, s0
	s_addc_u32 s3, s3, 0
	s_add_u32 s60, s26, s2
	s_addc_u32 s61, s27, s3
	s_add_u32 s60, s60, 0x0
	s_addc_u32 s61, s61, 0
	s_cmp_eq_u32 s65, 0
	s_cbranch_scc1 .Lg2_win_k2
	s_add_u32 s4, s56, 0x0
	s_addc_u32 s5, s57, 0
	s_add_u32 m0, s62, 0x0
	s_nop 0
	global_load_lds_dwordx4 v162, s[4:5]
	s_cmp_gt_u32 s70, 1
	s_cbranch_scc1 .Lg2_win_nodma_3
	s_add_u32 s4, s56, 0x10000
	s_addc_u32 s5, s57, 0
	s_add_u32 m0, s62, 0x1000
	s_nop 0
	global_load_lds_dwordx4 v162, s[4:5]
.Lg2_win_nodma_3:
	global_load_dwordx4 v[184:187], v160, s[58:59] offset:0
	global_load_dwordx4 v[188:191], v160, s[58:59] offset:1024
	global_load_dwordx4 v[192:195], v161, s[58:59] offset:0
	global_load_dwordx4 v[196:199], v161, s[58:59] offset:1024
	v_mov_b32_e32 v0, 0
	v_mov_b32_e32 v1, 0
	v_mov_b32_e32 v2, 0
	v_mov_b32_e32 v3, 0
	v_mov_b32_e32 v4, 0
	v_mov_b32_e32 v5, 0
	v_mov_b32_e32 v6, 0
	v_mov_b32_e32 v7, 0
	v_mov_b32_e32 v8, 0
	v_mov_b32_e32 v9, 0
	v_mov_b32_e32 v10, 0
	v_mov_b32_e32 v11, 0
	v_mov_b32_e32 v12, 0
	v_mov_b32_e32 v13, 0
	v_mov_b32_e32 v14, 0
	v_mov_b32_e32 v15, 0
	v_mov_b32_e32 v16, 0
	v_mov_b32_e32 v17, 0
	v_mov_b32_e32 v18, 0
	v_mov_b32_e32 v19, 0
	v_mov_b32_e32 v20, 0
	v_mov_b32_e32 v21, 0
	v_mov_b32_e32 v22, 0
	v_mov_b32_e32 v23, 0
	s_mov_b32 s63, 0

.Lg2_win_k2:
	s_add_u32 s4, s56, 0x0
	s_addc_u32 s5, s57, 0
	s_add_u32 m0, s62, 0x0
	s_nop 0
	global_load_lds_dwordx4 v162, s[4:5]
	global_load_dwordx4 v[184:187], v160, s[58:59] offset:0
	global_load_dwordx4 v[188:191], v160, s[58:59] offset:1024
	global_load_dwordx4 v[192:195], v161, s[58:59] offset:0
	global_load_dwordx4 v[196:199], v161, s[58:59] offset:1024
	v_mov_b32_e32 v0, 0
	v_mov_b32_e32 v1, 0
	v_mov_b32_e32 v2, 0
	v_mov_b32_e32 v3, 0
	v_mov_b32_e32 v4, 0
	v_mov_b32_e32 v5, 0
	v_mov_b32_e32 v6, 0
	v_mov_b32_e32 v7, 0
	v_mov_b32_e32 v8, 0
	v_mov_b32_e32 v9, 0
	v_mov_b32_e32 v10, 0
	v_mov_b32_e32 v11, 0
	v_mov_b32_e32 v12, 0
	v_mov_b32_e32 v13, 0
	v_mov_b32_e32 v14, 0
	v_mov_b32_e32 v15, 0
	s_mov_b32 s63, 0
